# GLA out-norm: o_f/gate loads of heads 1..3 issued with the row's first loads (3 fewer exposed round trips per row), on top of v33
# speedup vs baseline: 1.0362x; 1.0112x over previous
; __device__ __forceinline__ void gla_onorm_phase(const Ctx& c, int j) {
;     ...
;     for (int row = gw; row < MV; row += NGW) {
; #pragma unroll
;         for (int hh = 0; hh < 4; ++hh) {
;             const int col = hh * 512 + c.lane * 8;
;             const u32x4 a = *(const u32x4*)(P + (size_t)row * GLA_NP + col), bq = *(const u32x4*)(A + (size_t)row * DM + col), gq = *(const u32x4*)(P + (size_t)row * GLA_NP + 4096 + col);
;             const unsigned aw[4] = {a.x, a.y, a.z, a.w}, bw[4] = {bq.x, bq.y, bq.z, bq.w}, gw4[4] = {gq.x, gq.y, gq.z, gq.w};
;             float o[8], g[8]; float ss = 0.f;
; #pragma unroll
;             for (int e = 0; e < 4; ++e) {
;                 o[2 * e] = __uint_as_float(aw[e] << 16) + __uint_as_float(bw[e] << 16); o[2 * e + 1] = __uint_as_float(aw[e] & 0xffff0000u) + __uint_as_float(bw[e] & 0xffff0000u);
;                 g[2 * e] = __uint_as_float(gw4[e] << 16); g[2 * e + 1] = __uint_as_float(gw4[e] & 0xffff0000u);
;                 ss += o[2 * e] * o[2 * e] + o[2 * e + 1] * o[2 * e + 1]; }
;             const float rstd = 1.0f / sqrtf(wave_sum(ss) * (1.f / 512.f) + NORM_EPS);
.LBB0_857:
	v_lshl_add_u64 v[10:11], s[28:29], 0, v[8:9]
	v_add_co_u32_e32 v14, vcc, 0x6300000, v10
	v_lshl_add_u64 v[12:13], s[24:25], 0, v[8:9]
	s_nop 0
	v_addc_co_u32_e32 v15, vcc, 0, v11, vcc
	v_add_co_u32_e32 v12, vcc, 0x2200000, v12
	global_load_dwordx4 v[24:27], v[14:15], off
	s_nop 0
	v_addc_co_u32_e32 v13, vcc, 0, v13, vcc
	v_add_co_u32_e32 v10, vcc, 0x6302000, v10
	global_load_dwordx4 v[28:31], v[12:13], off
	global_load_dwordx4 v[32:35], v[12:13], off offset:1024
	global_load_dwordx4 v[36:39], v[12:13], off offset:2048
	global_load_dwordx4 v[40:43], v[12:13], off offset:3072
	v_addc_co_u32_e32 v11, vcc, 0, v11, vcc
	global_load_dwordx4 v[44:47], v[10:11], off
	global_load_dwordx4 v[116:119], v[14:15], off offset:1024
	global_load_dwordx4 v[120:123], v[10:11], off offset:1024
	global_load_dwordx4 v[124:127], v[14:15], off offset:2048
	global_load_dwordx4 v[128:131], v[10:11], off offset:2048
	global_load_dwordx4 v[132:135], v[14:15], off offset:3072
	global_load_dwordx4 v[136:139], v[10:11], off offset:3072
	s_add_i32 s20, s20, s22
	s_add_u32 s24, s24, s26
	s_addc_u32 s25, s25, s27
	s_add_u32 s28, s28, s0
	s_addc_u32 s29, s29, s1
	s_cmpk_lt_i32 s20, 0x4040
	s_waitcnt vmcnt(11)
	v_and_b32_e32 v49, 0xffff0000, v24
	v_and_b32_e32 v51, 0xffff0000, v25
	s_waitcnt vmcnt(10)
	v_and_b32_e32 v57, 0xffff0000, v28
	v_and_b32_e32 v59, 0xffff0000, v29
	v_lshlrev_b32_e32 v48, 16, v24
	v_lshlrev_b32_e32 v50, 16, v25
	v_and_b32_e32 v53, 0xffff0000, v26
	v_lshlrev_b32_e32 v56, 16, v28
	v_lshlrev_b32_e32 v58, 16, v29
	v_and_b32_e32 v61, 0xffff0000, v30
	s_waitcnt vmcnt(9)
	v_lshlrev_b32_e32 v66, 16, v33
	v_and_b32_e32 v67, 0xffff0000, v33
	s_waitcnt vmcnt(8)
	v_lshlrev_b32_e32 v74, 16, v37
	v_and_b32_e32 v75, 0xffff0000, v37
	v_add_f32_e32 v33, v57, v49
	v_add_f32_e32 v37, v59, v51
	v_lshlrev_b32_e32 v52, 16, v26
	v_lshlrev_b32_e32 v54, 16, v27
	v_and_b32_e32 v55, 0xffff0000, v27
	v_lshlrev_b32_e32 v60, 16, v30
	v_and_b32_e32 v63, 0xffff0000, v31
	v_lshlrev_b32_e32 v64, 16, v32
	v_and_b32_e32 v65, 0xffff0000, v32
	v_lshlrev_b32_e32 v68, 16, v34
	v_and_b32_e32 v69, 0xffff0000, v34
	v_lshlrev_b32_e32 v70, 16, v35
	v_and_b32_e32 v71, 0xffff0000, v35
	v_lshlrev_b32_e32 v72, 16, v36
	v_and_b32_e32 v73, 0xffff0000, v36
	v_lshlrev_b32_e32 v78, 16, v39
	v_and_b32_e32 v79, 0xffff0000, v39
	s_waitcnt vmcnt(7)
	v_lshlrev_b32_e32 v26, 16, v41
	v_and_b32_e32 v27, 0xffff0000, v41
	v_add_f32_e32 v32, v56, v48
	s_waitcnt vmcnt(6)
	v_lshlrev_b32_e32 v34, 16, v44
	v_and_b32_e32 v35, 0xffff0000, v44
	v_add_f32_e32 v36, v58, v50
	v_and_b32_e32 v39, 0xffff0000, v45
	v_add_f32_e32 v41, v61, v53
	v_mul_f32_e32 v48, v37, v37
	v_mul_f32_e32 v49, v33, v33
	v_lshlrev_b32_e32 v62, 16, v31
	v_lshlrev_b32_e32 v76, 16, v38
	v_and_b32_e32 v77, 0xffff0000, v38
	v_lshlrev_b32_e32 v24, 16, v40
	v_and_b32_e32 v25, 0xffff0000, v40
	v_lshlrev_b32_e32 v28, 16, v42
	v_and_b32_e32 v29, 0xffff0000, v42
	v_lshlrev_b32_e32 v30, 16, v43
	v_and_b32_e32 v31, 0xffff0000, v43
	v_lshlrev_b32_e32 v38, 16, v45
	v_add_f32_e32 v40, v60, v52
	v_lshlrev_b32_e32 v42, 16, v46
	v_and_b32_e32 v43, 0xffff0000, v46
	v_add_f32_e32 v45, v63, v55
	v_lshlrev_b32_e32 v46, 16, v47
	v_mul_f32_e32 v50, v41, v41
	v_mul_f32_e32 v52, 0xbfb8aa3b, v34
	v_mul_f32_e32 v53, 0xbfb8aa3b, v35
	v_mul_f32_e32 v55, 0xbfb8aa3b, v39
	v_fmac_f32_e32 v48, v36, v36
	v_fmac_f32_e32 v49, v32, v32
	v_add_f32_e32 v44, v62, v54
	v_mul_f32_e32 v51, v45, v45
	v_mul_f32_e32 v54, 0xbfb8aa3b, v38
	v_mul_f32_e32 v56, 0xbfb8aa3b, v42
	v_mul_f32_e32 v58, 0xbfb8aa3b, v46
	v_fmac_f32_e32 v50, v40, v40
	v_exp_f32_e32 v52, v52
	v_exp_f32_e32 v53, v53
	v_exp_f32_e32 v55, v55
	v_add_f32_e32 v48, v49, v48
	v_fmac_f32_e32 v51, v44, v44
	v_exp_f32_e32 v54, v54
	v_exp_f32_e32 v56, v56
	v_exp_f32_e32 v58, v58
	v_add_f32_e32 v48, v50, v48
	v_add_f32_e32 v48, v51, v48
	ds_bpermute_b32 v49, v16, v48
	v_add_f32_e32 v50, 1.0, v52
	v_add_f32_e32 v51, 1.0, v53
	v_add_f32_e32 v53, 1.0, v55
	v_and_b32_e32 v47, 0xffff0000, v47
	v_add_f32_e32 v52, 1.0, v54
	v_add_f32_e32 v54, 1.0, v56
	v_add_f32_e32 v56, 1.0, v58
	v_div_scale_f32 v58, s[2:3], v50, v50, v34
	v_div_scale_f32 v60, s[2:3], v51, v51, v35
	v_div_scale_f32 v80, s[2:3], v53, v53, v39
	v_mul_f32_e32 v57, 0xbfb8aa3b, v43
	v_mul_f32_e32 v59, 0xbfb8aa3b, v47
	v_rcp_f32_e32 v90, v58
	v_rcp_f32_e32 v91, v60
	v_rcp_f32_e32 v93, v80
	v_exp_f32_e32 v57, v57
	v_exp_f32_e32 v59, v59
	s_waitcnt lgkmcnt(0)
	v_add_f32_e32 v48, v48, v49
	ds_bpermute_b32 v49, v17, v48
	v_fma_f32 v98, -v58, v90, 1.0
	v_fma_f32 v99, -v60, v91, 1.0
	v_fma_f32 v101, -v80, v93, 1.0
	v_add_f32_e32 v55, 1.0, v57
	v_add_f32_e32 v57, 1.0, v59
	v_div_scale_f32 v59, s[16:17], v34, v50, v34
	v_div_scale_f32 v61, s[14:15], v35, v51, v35
	v_div_scale_f32 v81, s[10:11], v39, v53, v39
	v_fmac_f32_e32 v90, v98, v90
	v_fmac_f32_e32 v91, v99, v91
	v_fmac_f32_e32 v93, v101, v93
	v_mul_f32_e32 v98, v59, v90
	v_mul_f32_e32 v99, v61, v91
	v_mul_f32_e32 v101, v81, v93
	v_fma_f32 v106, -v58, v98, v59
	v_fma_f32 v107, -v60, v99, v61
	v_fma_f32 v109, -v80, v101, v81
	v_fmac_f32_e32 v98, v106, v90
	v_fmac_f32_e32 v99, v107, v91
	v_fmac_f32_e32 v101, v109, v93
	s_waitcnt lgkmcnt(0)
	v_add_f32_e32 v48, v48, v49
	v_fma_f32 v49, -v58, v98, v59
	v_fma_f32 v58, -v60, v99, v61
	v_fma_f32 v60, -v80, v101, v81
	ds_bpermute_b32 v81, v18, v48
	v_div_scale_f32 v82, s[2:3], v54, v54, v42
	v_div_scale_f32 v62, s[2:3], v52, v52, v38
	s_waitcnt lgkmcnt(0)
	v_add_f32_e32 v48, v48, v81
	ds_bpermute_b32 v81, v19, v48
	v_div_scale_f32 v84, s[2:3], v55, v55, v43
	v_rcp_f32_e32 v94, v82
	v_rcp_f32_e32 v92, v62
	s_waitcnt lgkmcnt(0)
; __device__ __forceinline__ unsigned pk2(float lo, float hi) { unsigned r; asm("v_cvt_pk_bf16_f32 %0, %1, %2" : "=v"(r) : "v"(lo), "v"(hi)); return r; }
; __device__ __forceinline__ void gla_onorm_phase(const Ctx& c, int j) {
;     ...
;             const u32x4 a = *(const u32x4*)(P + (size_t)row * GLA_NP + col), bq = *(const u32x4*)(A + (size_t)row * DM + col), gq = *(const u32x4*)(P + (size_t)row * GLA_NP + 4096 + col);
;             const unsigned aw[4] = {a.x, a.y, a.z, a.w}, bw[4] = {bq.x, bq.y, bq.z, bq.w}, gw4[4] = {gq.x, gq.y, gq.z, gq.w};
;             float o[8], g[8]; float ss = 0.f;
; #pragma unroll
;             for (int e = 0; e < 4; ++e) {
;                 o[2 * e] = __uint_as_float(aw[e] << 16) + __uint_as_float(bw[e] << 16); o[2 * e + 1] = __uint_as_float(aw[e] & 0xffff0000u) + __uint_as_float(bw[e] & 0xffff0000u);
;                 g[2 * e] = __uint_as_float(gw4[e] << 16); g[2 * e + 1] = __uint_as_float(gw4[e] & 0xffff0000u);
;                 ss += o[2 * e] * o[2 * e] + o[2 * e + 1] * o[2 * e + 1]; }
;             const float rstd = 1.0f / sqrtf(wave_sum(ss) * (1.f / 512.f) + NORM_EPS);
;             float r[8];
; #pragma unroll
;             for (int e = 0; e < 8; ++e) r[e] = o[e] * rstd * w8[e] * (g[e] / (1.f + __expf(-g[e])));
;             u32x4 w; w.x = pk2(r[0], r[1]); w.y = pk2(r[2], r[3]); w.z = pk2(r[4], r[5]); w.w = pk2(r[6], r[7]);
;             *(u32x4*)(A + (size_t)row * DM + col) = w;
	v_add_f32_e32 v48, v48, v81
	ds_bpermute_b32 v81, v20, v48
	v_rcp_f32_e32 v95, v84
	v_fma_f32 v102, -v82, v94, 1.0
	v_div_scale_f32 v83, s[8:9], v42, v54, v42
	s_waitcnt lgkmcnt(0)
	v_add_f32_e32 v48, v48, v81
	ds_bpermute_b32 v81, v21, v48
	v_fma_f32 v100, -v62, v92, 1.0
	v_fma_f32 v103, -v84, v95, 1.0
	v_fmac_f32_e32 v94, v102, v94
	v_div_scale_f32 v63, s[12:13], v38, v52, v38
	s_waitcnt lgkmcnt(0)
	v_add_f32_e32 v48, v48, v81
	v_fmamk_f32 v48, v48, 0x3b000000, v22
	v_mul_f32_e32 v81, 0x4f800000, v48
	v_cmp_gt_f32_e32 vcc, s21, v48
	v_div_scale_f32 v85, s[6:7], v43, v55, v43
	s_nop 0
	v_cndmask_b32_e32 v48, v48, v81, vcc
	v_sqrt_f32_e32 v81, v48
	v_fmac_f32_e32 v92, v100, v92
	v_fmac_f32_e32 v95, v103, v95
	v_mul_f32_e32 v102, v83, v94
	v_mul_f32_e32 v100, v63, v92
	v_mul_f32_e32 v103, v85, v95
	v_fma_f32 v110, -v82, v102, v83
	v_fma_f32 v108, -v62, v100, v63
	v_fma_f32 v111, -v84, v103, v85
	v_fmac_f32_e32 v102, v110, v94
	v_fmac_f32_e32 v100, v108, v92
	v_fmac_f32_e32 v103, v111, v95
	v_fma_f32 v61, -v82, v102, v83
	v_add_u32_e32 v82, -1, v81
	v_fma_f32 v59, -v62, v100, v63
	v_fma_f32 v62, -v84, v103, v85
	v_add_u32_e32 v83, 1, v81
	v_fma_f32 v84, -v82, v81, v48
	v_fma_f32 v85, -v83, v81, v48
	v_cmp_ge_f32_e64 s[18:19], 0, v84
	v_div_scale_f32 v86, s[2:3], v56, v56, v46
	s_nop 0
	v_cndmask_b32_e64 v81, v81, v82, s[18:19]
	v_cmp_lt_f32_e64 s[18:19], 0, v85
	v_div_scale_f32 v88, s[2:3], v57, v57, v47
	s_nop 0
	v_cndmask_b32_e64 v81, v81, v83, s[18:19]
	v_mul_f32_e32 v82, 0x37800000, v81
	v_cndmask_b32_e32 v81, v81, v82, vcc
	v_cmp_class_f32_e32 vcc, v48, v23
	v_rcp_f32_e32 v96, v86
	v_rcp_f32_e32 v97, v88
	v_cndmask_b32_e32 v48, v81, v48, vcc
	v_div_scale_f32 v81, s[18:19], v48, v48, 1.0
	v_rcp_f32_e32 v83, v81
	v_div_scale_f32 v82, vcc, 1.0, v48, 1.0
	v_fma_f32 v104, -v86, v96, 1.0
	v_fma_f32 v84, -v81, v83, 1.0
	v_fmac_f32_e32 v83, v84, v83
	v_mul_f32_e32 v84, v82, v83
	v_fma_f32 v85, -v81, v84, v82
	v_fmac_f32_e32 v84, v85, v83
	v_fma_f32 v81, -v81, v84, v82
	v_div_fmas_f32 v81, v81, v83, v84
	s_mov_b64 vcc, s[16:17]
	v_div_fixup_f32 v48, v81, v48, 1.0
	v_div_fmas_f32 v49, v49, v90, v98
	s_mov_b64 vcc, s[14:15]
	v_div_scale_f32 v87, s[4:5], v46, v56, v46
	v_fma_f32 v105, -v88, v97, 1.0
	v_fmac_f32_e32 v96, v104, v96
	v_mul_f32_e32 v32, v32, v48
	v_div_fixup_f32 v34, v49, v50, v34
	v_mul_f32_e32 v33, v33, v48
	v_div_fmas_f32 v49, v58, v91, v99
	s_mov_b64 vcc, s[12:13]
	v_div_scale_f32 v89, s[2:3], v47, v57, v47
	v_fmac_f32_e32 v97, v105, v97
	v_mul_f32_e32 v104, v87, v96
	v_mul_f32_e32 v36, v36, v48
	v_mul_f32_e32 v37, v37, v48
	v_mul_f32_e32 v40, v40, v48
	v_mul_f32_e32 v41, v41, v48
	v_mul_f32_e32 v44, v44, v48
	v_mul_f32_e32 v45, v45, v48
	v_mul_f32_e32 v32, v0, v32
	v_mul_f32_e32 v33, v1, v33
	v_div_fixup_f32 v35, v49, v51, v35
	v_div_fmas_f32 v48, v59, v92, v100
	s_mov_b64 vcc, s[10:11]
	v_mul_f32_e32 v105, v89, v97
	v_fma_f32 v112, -v86, v104, v87
	v_mul_f32_e32 v36, v2, v36
	v_mul_f32_e32 v32, v34, v32
	v_mul_f32_e32 v33, v35, v33
	v_div_fixup_f32 v34, v48, v52, v38
	v_div_fmas_f32 v35, v60, v93, v101
	s_mov_b64 vcc, s[8:9]
	v_fma_f32 v113, -v88, v105, v89
	v_fmac_f32_e32 v104, v112, v96
	v_mul_f32_e32 v37, v3, v37
	v_mul_f32_e32 v34, v34, v36
	v_div_fixup_f32 v35, v35, v53, v39
	v_div_fmas_f32 v36, v61, v94, v102
	s_mov_b64 vcc, s[6:7]
	v_fmac_f32_e32 v105, v113, v97
	v_fma_f32 v63, -v86, v104, v87
	v_cvt_pk_bf16_f32 v32, v32, v33
	v_mul_f32_e32 v33, v35, v37
	v_div_fixup_f32 v35, v36, v54, v42
	v_div_fmas_f32 v36, v62, v95, v103
	s_mov_b64 vcc, s[4:5]
	v_fma_f32 v80, -v88, v105, v89
	v_mul_f32_e32 v41, v5, v41
	v_div_fixup_f32 v36, v36, v55, v43
	v_div_fmas_f32 v37, v63, v96, v104
	s_mov_b64 vcc, s[2:3]
	v_mul_f32_e32 v40, v4, v40
	v_cvt_pk_bf16_f32 v33, v34, v33
	v_mul_f32_e32 v34, v36, v41
	v_div_fixup_f32 v36, v37, v56, v46
	v_div_fmas_f32 v37, v80, v97, v105
	v_mul_f32_e32 v45, v7, v45
	v_mul_f32_e32 v35, v35, v40
	v_div_fixup_f32 v37, v37, v57, v47
	v_mul_f32_e32 v44, v6, v44
	v_cvt_pk_bf16_f32 v34, v35, v34
	v_mul_f32_e32 v35, v37, v45
	v_mul_f32_e32 v36, v36, v44
	v_cvt_pk_bf16_f32 v35, v36, v35
	global_store_dwordx4 v[12:13], v[32:35], off
	s_waitcnt vmcnt(5)
	s_nop 1
	v_mov_b64_e32 v[32:33], v[116:117]
	v_mov_b64_e32 v[34:35], v[118:119]
	s_nop 0
	v_mov_b64_e32 v[36:37], v[120:121]
	v_mov_b64_e32 v[38:39], v[122:123]
	v_lshlrev_b32_e32 v40, 16, v32
	v_and_b32_e32 v32, 0xffff0000, v32
	v_lshlrev_b32_e32 v42, 16, v33
	v_and_b32_e32 v33, 0xffff0000, v33
	v_lshlrev_b32_e32 v44, 16, v34
	v_and_b32_e32 v34, 0xffff0000, v34
	v_add_f32_e32 v32, v65, v32
	v_add_f32_e32 v33, v67, v33
	v_lshlrev_b32_e32 v41, 16, v36
	v_and_b32_e32 v36, 0xffff0000, v36
	v_lshlrev_b32_e32 v43, 16, v37
	v_lshlrev_b32_e32 v45, 16, v38
	v_lshlrev_b32_e32 v46, 16, v35
	v_and_b32_e32 v35, 0xffff0000, v35
	v_add_f32_e32 v40, v64, v40
	v_add_f32_e32 v42, v66, v42
	v_add_f32_e32 v34, v69, v34
	v_mul_f32_e32 v56, v33, v33
	v_mul_f32_e32 v57, v32, v32
	v_add_f32_e32 v44, v68, v44
	v_add_f32_e32 v35, v71, v35
	v_mul_f32_e32 v48, 0xbfb8aa3b, v41
	v_mul_f32_e32 v49, 0xbfb8aa3b, v36
	v_mul_f32_e32 v50, 0xbfb8aa3b, v43
	v_mul_f32_e32 v52, 0xbfb8aa3b, v45
	v_mul_f32_e32 v58, v34, v34
	v_fmac_f32_e32 v56, v42, v42
	v_fmac_f32_e32 v57, v40, v40
	v_add_f32_e32 v46, v70, v46
	v_mul_f32_e32 v59, v35, v35
	v_exp_f32_e32 v48, v48
	v_exp_f32_e32 v49, v49
	v_exp_f32_e32 v50, v50
	v_exp_f32_e32 v52, v52
	v_fmac_f32_e32 v58, v44, v44
	v_add_f32_e32 v56, v57, v56
	v_fmac_f32_e32 v59, v46, v46
	v_add_f32_e32 v56, v58, v56
	v_add_f32_e32 v56, v59, v56
	ds_bpermute_b32 v57, v16, v56
	v_add_f32_e32 v48, 1.0, v48
	v_add_f32_e32 v49, 1.0, v49
	v_add_f32_e32 v50, 1.0, v50
	v_add_f32_e32 v52, 1.0, v52
	v_div_scale_f32 v58, s[2:3], v48, v48, v41
	v_div_scale_f32 v60, s[2:3], v49, v49, v36
	v_div_scale_f32 v62, s[2:3], v50, v50, v43
	v_div_scale_f32 v66, s[2:3], v52, v52, v45
	v_rcp_f32_e32 v82, v58
	v_rcp_f32_e32 v83, v60
	v_rcp_f32_e32 v84, v62
	v_rcp_f32_e32 v86, v66
	s_waitcnt lgkmcnt(0)
; __device__ __forceinline__ unsigned pk2(float lo, float hi) { unsigned r; asm("v_cvt_pk_bf16_f32 %0, %1, %2" : "=v"(r) : "v"(lo), "v"(hi)); return r; }
; __device__ __forceinline__ void gla_onorm_phase(const Ctx& c, int j) {
;     ...
;             const u32x4 a = *(const u32x4*)(P + (size_t)row * GLA_NP + col), bq = *(const u32x4*)(A + (size_t)row * DM + col), gq = *(const u32x4*)(P + (size_t)row * GLA_NP + 4096 + col);
;             const unsigned aw[4] = {a.x, a.y, a.z, a.w}, bw[4] = {bq.x, bq.y, bq.z, bq.w}, gw4[4] = {gq.x, gq.y, gq.z, gq.w};
;             float o[8], g[8]; float ss = 0.f;
; #pragma unroll
;             for (int e = 0; e < 4; ++e) {
;                 o[2 * e] = __uint_as_float(aw[e] << 16) + __uint_as_float(bw[e] << 16); o[2 * e + 1] = __uint_as_float(aw[e] & 0xffff0000u) + __uint_as_float(bw[e] & 0xffff0000u);
;                 g[2 * e] = __uint_as_float(gw4[e] << 16); g[2 * e + 1] = __uint_as_float(gw4[e] & 0xffff0000u);
;                 ss += o[2 * e] * o[2 * e] + o[2 * e + 1] * o[2 * e + 1]; }
;             const float rstd = 1.0f / sqrtf(wave_sum(ss) * (1.f / 512.f) + NORM_EPS);
;             float r[8];
; #pragma unroll
;             for (int e = 0; e < 8; ++e) r[e] = o[e] * rstd * w8[e] * (g[e] / (1.f + __expf(-g[e])));
;             u32x4 w; w.x = pk2(r[0], r[1]); w.y = pk2(r[2], r[3]); w.z = pk2(r[4], r[5]); w.w = pk2(r[6], r[7]);
;             *(u32x4*)(A + (size_t)row * DM + col) = w;
	v_add_f32_e32 v56, v56, v57
	ds_bpermute_b32 v97, v17, v56
	v_fma_f32 v57, -v58, v82, 1.0
	v_fma_f32 v90, -v60, v83, 1.0
	v_fma_f32 v91, -v62, v84, 1.0
	v_fma_f32 v93, -v66, v86, 1.0
	v_div_scale_f32 v59, s[16:17], v41, v48, v41
	v_div_scale_f32 v61, s[14:15], v36, v49, v36
	v_div_scale_f32 v63, s[12:13], v43, v50, v43
	v_div_scale_f32 v67, s[8:9], v45, v52, v45
	v_fmac_f32_e32 v82, v57, v82
	v_fmac_f32_e32 v83, v90, v83
	v_fmac_f32_e32 v84, v91, v84
	v_fmac_f32_e32 v86, v93, v86
	v_mul_f32_e32 v57, v59, v82
	v_mul_f32_e32 v90, v61, v83
	v_mul_f32_e32 v91, v63, v84
	v_mul_f32_e32 v93, v67, v86
	v_fma_f32 v98, -v58, v57, v59
	v_fma_f32 v99, -v60, v90, v61
	v_fma_f32 v100, -v62, v91, v63
	v_fma_f32 v102, -v66, v93, v67
	v_fmac_f32_e32 v57, v98, v82
	v_fmac_f32_e32 v90, v99, v83
	v_fmac_f32_e32 v91, v100, v84
	v_fmac_f32_e32 v93, v102, v86
	s_waitcnt lgkmcnt(0)
	v_add_f32_e32 v56, v56, v97
	v_fma_f32 v58, -v58, v57, v59
	v_fma_f32 v59, -v60, v90, v61
	v_fma_f32 v60, -v62, v91, v63
	v_fma_f32 v62, -v66, v93, v67
	ds_bpermute_b32 v66, v18, v56
	v_and_b32_e32 v38, 0xffff0000, v38
	v_and_b32_e32 v37, 0xffff0000, v37
	v_lshlrev_b32_e32 v47, 16, v39
	v_mul_f32_e32 v53, 0xbfb8aa3b, v38
	s_waitcnt lgkmcnt(0)
	v_add_f32_e32 v56, v56, v66
	ds_bpermute_b32 v66, v19, v56
	v_mul_f32_e32 v51, 0xbfb8aa3b, v37
	v_mul_f32_e32 v54, 0xbfb8aa3b, v47
	v_exp_f32_e32 v53, v53
	v_exp_f32_e32 v51, v51
	s_waitcnt lgkmcnt(0)
	v_add_f32_e32 v56, v56, v66
	ds_bpermute_b32 v66, v20, v56
	v_exp_f32_e32 v54, v54
	v_add_f32_e32 v53, 1.0, v53
	v_add_f32_e32 v51, 1.0, v51
	v_div_scale_f32 v68, s[2:3], v53, v53, v38
	s_waitcnt lgkmcnt(0)
	v_add_f32_e32 v56, v56, v66
	ds_bpermute_b32 v66, v21, v56
	v_add_f32_e32 v54, 1.0, v54
	v_div_scale_f32 v64, s[2:3], v51, v51, v37
	v_div_scale_f32 v70, s[2:3], v54, v54, v47
	v_rcp_f32_e32 v87, v68
	s_waitcnt lgkmcnt(0)
	v_add_f32_e32 v56, v56, v66
	v_rcp_f32_e32 v85, v64
	v_rcp_f32_e32 v88, v70
	v_fmamk_f32 v56, v56, 0x3b000000, v22
	v_mul_f32_e32 v66, 0x4f800000, v56
	v_cmp_gt_f32_e32 vcc, s21, v56
	v_fma_f32 v94, -v68, v87, 1.0
	v_div_scale_f32 v69, s[6:7], v38, v53, v38
	v_cndmask_b32_e32 v56, v56, v66, vcc
	v_sqrt_f32_e32 v66, v56
	v_fma_f32 v92, -v64, v85, 1.0
	v_fma_f32 v95, -v70, v88, 1.0
	v_fmac_f32_e32 v87, v94, v87
	v_div_scale_f32 v65, s[10:11], v37, v51, v37
	v_div_scale_f32 v71, s[4:5], v47, v54, v47
	v_fmac_f32_e32 v85, v92, v85
	v_fmac_f32_e32 v88, v95, v88
	v_mul_f32_e32 v94, v69, v87
	v_mul_f32_e32 v92, v65, v85
	v_mul_f32_e32 v95, v71, v88
	v_fma_f32 v103, -v68, v94, v69
	v_fma_f32 v101, -v64, v92, v65
	v_fma_f32 v104, -v70, v95, v71
	v_fmac_f32_e32 v94, v103, v87
	v_add_u32_e32 v67, -1, v66
	v_fmac_f32_e32 v92, v101, v85
	v_fmac_f32_e32 v95, v104, v88
	v_fma_f32 v63, -v68, v94, v69
	v_add_u32_e32 v68, 1, v66
	v_fma_f32 v69, -v67, v66, v56
	v_fma_f32 v61, -v64, v92, v65
	v_fma_f32 v64, -v70, v95, v71
	v_fma_f32 v70, -v68, v66, v56
	v_cmp_ge_f32_e64 s[18:19], 0, v69
	v_and_b32_e32 v39, 0xffff0000, v39
	v_mul_f32_e32 v55, 0xbfb8aa3b, v39
	v_cndmask_b32_e64 v66, v66, v67, s[18:19]
	v_cmp_lt_f32_e64 s[18:19], 0, v70
	v_exp_f32_e32 v55, v55
	s_nop 0
	v_cndmask_b32_e64 v66, v66, v68, s[18:19]
	v_mul_f32_e32 v67, 0x37800000, v66
	v_cndmask_b32_e32 v66, v66, v67, vcc
	v_cmp_class_f32_e32 vcc, v56, v23
	v_add_f32_e32 v55, 1.0, v55
	v_div_scale_f32 v80, s[2:3], v55, v55, v39
	v_cndmask_b32_e32 v56, v66, v56, vcc
	v_div_scale_f32 v66, s[18:19], v56, v56, 1.0
	v_rcp_f32_e32 v68, v66
	v_div_scale_f32 v67, vcc, 1.0, v56, 1.0
	v_rcp_f32_e32 v89, v80
	v_fma_f32 v69, -v66, v68, 1.0
	v_fmac_f32_e32 v68, v69, v68
	v_mul_f32_e32 v69, v67, v68
	v_fma_f32 v70, -v66, v69, v67
	v_fmac_f32_e32 v69, v70, v68
	v_fma_f32 v66, -v66, v69, v67
	v_div_fmas_f32 v66, v66, v68, v69
	s_mov_b64 vcc, s[16:17]
	v_div_fixup_f32 v56, v66, v56, 1.0
	v_div_fmas_f32 v57, v58, v82, v57
	s_mov_b64 vcc, s[14:15]
	v_fma_f32 v96, -v80, v89, 1.0
	v_mul_f32_e32 v40, v40, v56
	v_div_fixup_f32 v41, v57, v48, v41
	v_div_fmas_f32 v48, v59, v83, v90
	s_mov_b64 vcc, s[12:13]
	v_div_scale_f32 v81, s[2:3], v39, v55, v39
	v_fmac_f32_e32 v89, v96, v89
	v_mul_f32_e32 v32, v32, v56
	v_mul_f32_e32 v40, v0, v40
	v_div_fixup_f32 v36, v48, v49, v36
	v_div_fmas_f32 v48, v60, v84, v91
	s_mov_b64 vcc, s[10:11]
	v_mul_f32_e32 v96, v81, v89
	v_mul_f32_e32 v32, v1, v32
	v_mul_f32_e32 v40, v41, v40
	v_div_fmas_f32 v41, v61, v85, v92
	s_mov_b64 vcc, s[8:9]
	v_fma_f32 v105, -v80, v96, v81
	v_mul_f32_e32 v32, v36, v32
	v_div_fixup_f32 v37, v41, v51, v37
	v_div_fmas_f32 v41, v62, v86, v93
	s_mov_b64 vcc, s[6:7]
	v_fmac_f32_e32 v96, v105, v89
	v_mul_f32_e32 v34, v34, v56
	v_cvt_pk_bf16_f32 v32, v40, v32
	v_div_fmas_f32 v40, v63, v87, v94
	s_mov_b64 vcc, s[4:5]
	v_fma_f32 v65, -v80, v96, v81
	v_mul_f32_e32 v42, v42, v56
	v_mul_f32_e32 v33, v33, v56
	v_mul_f32_e32 v34, v5, v34
	v_div_fixup_f32 v38, v40, v53, v38
	v_div_fmas_f32 v40, v64, v88, v95
	s_mov_b64 vcc, s[2:3]
	v_mul_f32_e32 v35, v35, v56
	v_mul_f32_e32 v42, v2, v42
	v_mul_f32_e32 v33, v3, v33
	v_div_fixup_f32 v36, v48, v50, v43
	v_mul_f32_e32 v34, v38, v34
	v_div_fmas_f32 v38, v65, v89, v96
	v_mul_f32_e32 v44, v44, v56
	v_mul_f32_e32 v46, v46, v56
	v_mul_f32_e32 v35, v7, v35
	v_mul_f32_e32 v36, v36, v42
	v_mul_f32_e32 v33, v37, v33
	v_div_fixup_f32 v38, v38, v55, v39
	v_mul_f32_e32 v44, v4, v44
	v_mul_f32_e32 v46, v6, v46
	v_div_fixup_f32 v37, v41, v52, v45
	v_cvt_pk_bf16_f32 v33, v36, v33
	v_div_fixup_f32 v36, v40, v54, v47
	v_mul_f32_e32 v35, v38, v35
	v_mul_f32_e32 v37, v37, v44
	v_mul_f32_e32 v36, v36, v46
	v_cvt_pk_bf16_f32 v34, v37, v34
	v_cvt_pk_bf16_f32 v35, v36, v35
	global_store_dwordx4 v[12:13], v[32:35], off offset:1024
	s_waitcnt vmcnt(4)
; __device__ __forceinline__ void gla_onorm_phase(const Ctx& c, int j) {
;     ...
;             const u32x4 a = *(const u32x4*)(P + (size_t)row * GLA_NP + col), bq = *(const u32x4*)(A + (size_t)row * DM + col), gq = *(const u32x4*)(P + (size_t)row * GLA_NP + 4096 + col);
;             const unsigned aw[4] = {a.x, a.y, a.z, a.w}, bw[4] = {bq.x, bq.y, bq.z, bq.w}, gw4[4] = {gq.x, gq.y, gq.z, gq.w};
;             float o[8], g[8]; float ss = 0.f;
; #pragma unroll
;             for (int e = 0; e < 4; ++e) {
;                 o[2 * e] = __uint_as_float(aw[e] << 16) + __uint_as_float(bw[e] << 16); o[2 * e + 1] = __uint_as_float(aw[e] & 0xffff0000u) + __uint_as_float(bw[e] & 0xffff0000u);
;                 g[2 * e] = __uint_as_float(gw4[e] << 16); g[2 * e + 1] = __uint_as_float(gw4[e] & 0xffff0000u);
;                 ss += o[2 * e] * o[2 * e] + o[2 * e + 1] * o[2 * e + 1]; }
;             const float rstd = 1.0f / sqrtf(wave_sum(ss) * (1.f / 512.f) + NORM_EPS);
;             float r[8];
; #pragma unroll
;             for (int e = 0; e < 8; ++e) r[e] = o[e] * rstd * w8[e] * (g[e] / (1.f + __expf(-g[e])));
	s_nop 1
	v_mov_b64_e32 v[32:33], v[124:125]
	v_mov_b64_e32 v[34:35], v[126:127]
	s_nop 0
	v_mov_b64_e32 v[36:37], v[128:129]
	v_mov_b64_e32 v[38:39], v[130:131]
	v_lshlrev_b32_e32 v40, 16, v32
	v_and_b32_e32 v32, 0xffff0000, v32
	v_lshlrev_b32_e32 v42, 16, v33
	v_and_b32_e32 v33, 0xffff0000, v33
	v_lshlrev_b32_e32 v44, 16, v34
	v_and_b32_e32 v34, 0xffff0000, v34
	v_add_f32_e32 v32, v73, v32
	v_add_f32_e32 v33, v75, v33
	v_lshlrev_b32_e32 v41, 16, v36
	v_and_b32_e32 v36, 0xffff0000, v36
	v_lshlrev_b32_e32 v43, 16, v37
	v_lshlrev_b32_e32 v45, 16, v38
	v_lshlrev_b32_e32 v46, 16, v35
	v_and_b32_e32 v35, 0xffff0000, v35
	v_add_f32_e32 v40, v72, v40
	v_add_f32_e32 v42, v74, v42
	v_add_f32_e32 v34, v77, v34
	v_mul_f32_e32 v56, v33, v33
	v_mul_f32_e32 v57, v32, v32
	v_add_f32_e32 v44, v76, v44
	v_add_f32_e32 v35, v79, v35
	v_mul_f32_e32 v48, 0xbfb8aa3b, v41
	v_mul_f32_e32 v49, 0xbfb8aa3b, v36
	v_mul_f32_e32 v50, 0xbfb8aa3b, v43
	v_mul_f32_e32 v52, 0xbfb8aa3b, v45
	v_mul_f32_e32 v58, v34, v34
	v_fmac_f32_e32 v56, v42, v42
	v_fmac_f32_e32 v57, v40, v40
	v_add_f32_e32 v46, v78, v46
	v_mul_f32_e32 v59, v35, v35
	v_exp_f32_e32 v48, v48
	v_exp_f32_e32 v49, v49
	v_exp_f32_e32 v50, v50
	v_exp_f32_e32 v52, v52
	v_fmac_f32_e32 v58, v44, v44
	v_add_f32_e32 v56, v57, v56
	v_fmac_f32_e32 v59, v46, v46
	v_add_f32_e32 v56, v58, v56
	v_add_f32_e32 v56, v59, v56
	ds_bpermute_b32 v57, v16, v56
	v_add_f32_e32 v48, 1.0, v48
	v_add_f32_e32 v49, 1.0, v49
	v_add_f32_e32 v50, 1.0, v50
	v_add_f32_e32 v52, 1.0, v52
	v_div_scale_f32 v58, s[2:3], v48, v48, v41
	v_div_scale_f32 v60, s[2:3], v49, v49, v36
	v_div_scale_f32 v62, s[2:3], v50, v50, v43
	v_div_scale_f32 v66, s[2:3], v52, v52, v45
	v_rcp_f32_e32 v74, v58
	v_rcp_f32_e32 v75, v60
	v_rcp_f32_e32 v76, v62
	v_rcp_f32_e32 v78, v66
	s_waitcnt lgkmcnt(0)
	v_add_f32_e32 v56, v56, v57
	ds_bpermute_b32 v89, v17, v56
	v_fma_f32 v57, -v58, v74, 1.0
	v_fma_f32 v82, -v60, v75, 1.0
	v_fma_f32 v83, -v62, v76, 1.0
	v_fma_f32 v85, -v66, v78, 1.0
	v_div_scale_f32 v59, s[16:17], v41, v48, v41
	v_div_scale_f32 v61, s[14:15], v36, v49, v36
	v_div_scale_f32 v63, s[12:13], v43, v50, v43
	v_div_scale_f32 v67, s[8:9], v45, v52, v45
	v_fmac_f32_e32 v74, v57, v74
	v_fmac_f32_e32 v75, v82, v75
	v_fmac_f32_e32 v76, v83, v76
	v_fmac_f32_e32 v78, v85, v78
	v_mul_f32_e32 v57, v59, v74
	v_mul_f32_e32 v82, v61, v75
	v_mul_f32_e32 v83, v63, v76
	v_mul_f32_e32 v85, v67, v78
	v_fma_f32 v90, -v58, v57, v59
	v_fma_f32 v91, -v60, v82, v61
	v_fma_f32 v92, -v62, v83, v63
	v_fma_f32 v94, -v66, v85, v67
	v_fmac_f32_e32 v57, v90, v74
	v_fmac_f32_e32 v82, v91, v75
	v_fmac_f32_e32 v83, v92, v76
	v_fmac_f32_e32 v85, v94, v78
	s_waitcnt lgkmcnt(0)
	v_add_f32_e32 v56, v56, v89
	v_fma_f32 v58, -v58, v57, v59
	v_fma_f32 v59, -v60, v82, v61
	v_fma_f32 v60, -v62, v83, v63
	v_fma_f32 v62, -v66, v85, v67
	ds_bpermute_b32 v66, v18, v56
	v_and_b32_e32 v38, 0xffff0000, v38
	v_and_b32_e32 v37, 0xffff0000, v37
	v_lshlrev_b32_e32 v47, 16, v39
	v_mul_f32_e32 v53, 0xbfb8aa3b, v38
	s_waitcnt lgkmcnt(0)
	v_add_f32_e32 v56, v56, v66
	ds_bpermute_b32 v66, v19, v56
	v_mul_f32_e32 v51, 0xbfb8aa3b, v37
	v_mul_f32_e32 v54, 0xbfb8aa3b, v47
	v_exp_f32_e32 v53, v53
	v_exp_f32_e32 v51, v51
	s_waitcnt lgkmcnt(0)
	v_add_f32_e32 v56, v56, v66
	ds_bpermute_b32 v66, v20, v56
	v_exp_f32_e32 v54, v54
	v_add_f32_e32 v53, 1.0, v53
	v_add_f32_e32 v51, 1.0, v51
	v_div_scale_f32 v68, s[2:3], v53, v53, v38
	s_waitcnt lgkmcnt(0)
	v_add_f32_e32 v56, v56, v66
	ds_bpermute_b32 v66, v21, v56
	v_add_f32_e32 v54, 1.0, v54
	v_div_scale_f32 v64, s[2:3], v51, v51, v37
	v_div_scale_f32 v70, s[2:3], v54, v54, v47
	v_rcp_f32_e32 v79, v68
	s_waitcnt lgkmcnt(0)
	v_add_f32_e32 v56, v56, v66
	v_rcp_f32_e32 v77, v64
	v_rcp_f32_e32 v80, v70
	v_fmamk_f32 v56, v56, 0x3b000000, v22
	v_mul_f32_e32 v66, 0x4f800000, v56
	v_cmp_gt_f32_e32 vcc, s21, v56
	v_fma_f32 v86, -v68, v79, 1.0
	v_div_scale_f32 v69, s[6:7], v38, v53, v38
	v_cndmask_b32_e32 v56, v56, v66, vcc
	v_sqrt_f32_e32 v66, v56
	v_fma_f32 v84, -v64, v77, 1.0
	v_fma_f32 v87, -v70, v80, 1.0
	v_fmac_f32_e32 v79, v86, v79
	v_div_scale_f32 v65, s[10:11], v37, v51, v37
	v_div_scale_f32 v71, s[4:5], v47, v54, v47
	v_fmac_f32_e32 v77, v84, v77
	v_fmac_f32_e32 v80, v87, v80
	v_mul_f32_e32 v86, v69, v79
	v_mul_f32_e32 v84, v65, v77
	v_mul_f32_e32 v87, v71, v80
	v_fma_f32 v95, -v68, v86, v69
	v_fma_f32 v93, -v64, v84, v65
	v_fma_f32 v96, -v70, v87, v71
	v_fmac_f32_e32 v86, v95, v79
	v_add_u32_e32 v67, -1, v66
	v_fmac_f32_e32 v84, v93, v77
	v_fmac_f32_e32 v87, v96, v80
	v_fma_f32 v63, -v68, v86, v69
	v_add_u32_e32 v68, 1, v66
	v_fma_f32 v69, -v67, v66, v56
	v_fma_f32 v61, -v64, v84, v65
	v_fma_f32 v64, -v70, v87, v71
	v_fma_f32 v70, -v68, v66, v56
	v_cmp_ge_f32_e64 s[18:19], 0, v69
	v_and_b32_e32 v39, 0xffff0000, v39
	v_mul_f32_e32 v55, 0xbfb8aa3b, v39
	v_cndmask_b32_e64 v66, v66, v67, s[18:19]
	v_cmp_lt_f32_e64 s[18:19], 0, v70
	v_exp_f32_e32 v55, v55
	s_nop 0
	v_cndmask_b32_e64 v66, v66, v68, s[18:19]
	v_mul_f32_e32 v67, 0x37800000, v66
	v_cndmask_b32_e32 v66, v66, v67, vcc
	v_cmp_class_f32_e32 vcc, v56, v23
	v_add_f32_e32 v55, 1.0, v55
	v_div_scale_f32 v72, s[2:3], v55, v55, v39
	v_cndmask_b32_e32 v56, v66, v56, vcc
	v_div_scale_f32 v66, s[18:19], v56, v56, 1.0
	v_rcp_f32_e32 v68, v66
	v_div_scale_f32 v67, vcc, 1.0, v56, 1.0
	v_rcp_f32_e32 v81, v72
	v_fma_f32 v69, -v66, v68, 1.0
	v_fmac_f32_e32 v68, v69, v68
	v_mul_f32_e32 v69, v67, v68
	v_fma_f32 v70, -v66, v69, v67
	v_fmac_f32_e32 v69, v70, v68
	v_fma_f32 v66, -v66, v69, v67
	v_div_fmas_f32 v66, v66, v68, v69
	s_mov_b64 vcc, s[16:17]
	v_div_fixup_f32 v56, v66, v56, 1.0
	v_div_fmas_f32 v57, v58, v74, v57
	s_mov_b64 vcc, s[14:15]
; __device__ __forceinline__ unsigned pk2(float lo, float hi) { unsigned r; asm("v_cvt_pk_bf16_f32 %0, %1, %2" : "=v"(r) : "v"(lo), "v"(hi)); return r; }
; __device__ __forceinline__ void gla_onorm_phase(const Ctx& c, int j) {
;     ...
;             const u32x4 a = *(const u32x4*)(P + (size_t)row * GLA_NP + col), bq = *(const u32x4*)(A + (size_t)row * DM + col), gq = *(const u32x4*)(P + (size_t)row * GLA_NP + 4096 + col);
;             const unsigned aw[4] = {a.x, a.y, a.z, a.w}, bw[4] = {bq.x, bq.y, bq.z, bq.w}, gw4[4] = {gq.x, gq.y, gq.z, gq.w};
;             float o[8], g[8]; float ss = 0.f;
; #pragma unroll
;             for (int e = 0; e < 4; ++e) {
;                 o[2 * e] = __uint_as_float(aw[e] << 16) + __uint_as_float(bw[e] << 16); o[2 * e + 1] = __uint_as_float(aw[e] & 0xffff0000u) + __uint_as_float(bw[e] & 0xffff0000u);
;                 g[2 * e] = __uint_as_float(gw4[e] << 16); g[2 * e + 1] = __uint_as_float(gw4[e] & 0xffff0000u);
;                 ss += o[2 * e] * o[2 * e] + o[2 * e + 1] * o[2 * e + 1]; }
;             const float rstd = 1.0f / sqrtf(wave_sum(ss) * (1.f / 512.f) + NORM_EPS);
;             float r[8];
; #pragma unroll
;             for (int e = 0; e < 8; ++e) r[e] = o[e] * rstd * w8[e] * (g[e] / (1.f + __expf(-g[e])));
;             u32x4 w; w.x = pk2(r[0], r[1]); w.y = pk2(r[2], r[3]); w.z = pk2(r[4], r[5]); w.w = pk2(r[6], r[7]);
;             *(u32x4*)(A + (size_t)row * DM + col) = w;
	v_fma_f32 v88, -v72, v81, 1.0
	v_mul_f32_e32 v40, v40, v56
	v_div_fixup_f32 v41, v57, v48, v41
	v_div_fmas_f32 v48, v59, v75, v82
	s_mov_b64 vcc, s[12:13]
	v_div_scale_f32 v73, s[2:3], v39, v55, v39
	v_fmac_f32_e32 v81, v88, v81
	v_mul_f32_e32 v32, v32, v56
	v_mul_f32_e32 v40, v0, v40
	v_div_fixup_f32 v36, v48, v49, v36
	v_div_fmas_f32 v48, v60, v76, v83
	s_mov_b64 vcc, s[10:11]
	v_mul_f32_e32 v88, v73, v81
	v_mul_f32_e32 v32, v1, v32
	v_mul_f32_e32 v40, v41, v40
	v_div_fmas_f32 v41, v61, v77, v84
	s_mov_b64 vcc, s[8:9]
	v_fma_f32 v97, -v72, v88, v73
	v_mul_f32_e32 v32, v36, v32
	v_div_fixup_f32 v37, v41, v51, v37
	v_div_fmas_f32 v41, v62, v78, v85
	s_mov_b64 vcc, s[6:7]
	v_fmac_f32_e32 v88, v97, v81
	v_mul_f32_e32 v34, v34, v56
	v_cvt_pk_bf16_f32 v32, v40, v32
	v_div_fmas_f32 v40, v63, v79, v86
	s_mov_b64 vcc, s[4:5]
	v_fma_f32 v65, -v72, v88, v73
	v_mul_f32_e32 v42, v42, v56
	v_mul_f32_e32 v33, v33, v56
	v_mul_f32_e32 v34, v5, v34
	v_div_fixup_f32 v38, v40, v53, v38
	v_div_fmas_f32 v40, v64, v80, v87
	s_mov_b64 vcc, s[2:3]
	v_mul_f32_e32 v35, v35, v56
	v_mul_f32_e32 v42, v2, v42
	v_mul_f32_e32 v33, v3, v33
	v_div_fixup_f32 v36, v48, v50, v43
	v_mul_f32_e32 v34, v38, v34
	v_div_fmas_f32 v38, v65, v81, v88
	v_mul_f32_e32 v44, v44, v56
	v_mul_f32_e32 v46, v46, v56
	v_mul_f32_e32 v35, v7, v35
	v_mul_f32_e32 v36, v36, v42
	v_mul_f32_e32 v33, v37, v33
	v_div_fixup_f32 v38, v38, v55, v39
	v_mul_f32_e32 v44, v4, v44
	v_mul_f32_e32 v46, v6, v46
	v_div_fixup_f32 v37, v41, v52, v45
	v_cvt_pk_bf16_f32 v33, v36, v33
	v_div_fixup_f32 v36, v40, v54, v47
	v_mul_f32_e32 v35, v38, v35
	v_mul_f32_e32 v37, v37, v44
	v_mul_f32_e32 v36, v36, v46
	v_cvt_pk_bf16_f32 v34, v37, v34
	v_cvt_pk_bf16_f32 v35, v36, v35
	global_store_dwordx4 v[12:13], v[32:35], off offset:2048
	s_waitcnt vmcnt(3)
	s_nop 1
	v_mov_b64_e32 v[32:33], v[132:133]
	v_mov_b64_e32 v[34:35], v[134:135]
	s_nop 0
	v_mov_b64_e32 v[36:37], v[136:137]
	v_mov_b64_e32 v[38:39], v[138:139]
	v_lshlrev_b32_e32 v10, 16, v32
	v_and_b32_e32 v11, 0xffff0000, v32
	v_lshlrev_b32_e32 v32, 16, v33
	v_and_b32_e32 v33, 0xffff0000, v33
	v_lshlrev_b32_e32 v40, 16, v34
	v_and_b32_e32 v34, 0xffff0000, v34
	v_add_f32_e32 v11, v25, v11
	v_add_f32_e32 v25, v27, v33
	v_lshlrev_b32_e32 v14, 16, v36
	v_and_b32_e32 v15, 0xffff0000, v36
	v_lshlrev_b32_e32 v36, 16, v37
	v_lshlrev_b32_e32 v41, 16, v38
	v_lshlrev_b32_e32 v42, 16, v35
	v_and_b32_e32 v35, 0xffff0000, v35
	v_add_f32_e32 v10, v24, v10
	v_add_f32_e32 v24, v26, v32
	v_add_f32_e32 v27, v29, v34
	v_mul_f32_e32 v44, v25, v25
	v_mul_f32_e32 v45, v11, v11
	v_add_f32_e32 v26, v28, v40
	v_add_f32_e32 v28, v30, v42
	v_add_f32_e32 v29, v31, v35
	v_mul_f32_e32 v30, 0xbfb8aa3b, v14
	v_mul_f32_e32 v31, 0xbfb8aa3b, v15
	v_mul_f32_e32 v32, 0xbfb8aa3b, v36
	v_mul_f32_e32 v34, 0xbfb8aa3b, v41
	v_mul_f32_e32 v46, v27, v27
	v_fmac_f32_e32 v44, v24, v24
	v_fmac_f32_e32 v45, v10, v10
	v_mul_f32_e32 v47, v29, v29
	v_exp_f32_e32 v30, v30
	v_exp_f32_e32 v31, v31
	v_exp_f32_e32 v32, v32
	v_exp_f32_e32 v34, v34
	v_fmac_f32_e32 v46, v26, v26
	v_add_f32_e32 v44, v45, v44
	v_fmac_f32_e32 v47, v28, v28
	v_add_f32_e32 v44, v46, v44
	v_add_f32_e32 v44, v47, v44
	ds_bpermute_b32 v45, v16, v44
	v_add_f32_e32 v30, 1.0, v30
	v_add_f32_e32 v31, 1.0, v31
	v_add_f32_e32 v32, 1.0, v32
	v_add_f32_e32 v34, 1.0, v34
	v_div_scale_f32 v46, s[2:3], v30, v30, v14
	v_div_scale_f32 v48, s[2:3], v31, v31, v15
	v_div_scale_f32 v50, s[2:3], v32, v32, v36
	v_div_scale_f32 v54, s[2:3], v34, v34, v41
	v_rcp_f32_e32 v62, v46
	v_rcp_f32_e32 v63, v48
	v_rcp_f32_e32 v64, v50
	v_rcp_f32_e32 v66, v54
	s_waitcnt lgkmcnt(0)
	v_add_f32_e32 v44, v44, v45
	ds_bpermute_b32 v77, v17, v44
	v_fma_f32 v45, -v46, v62, 1.0
	v_fma_f32 v70, -v48, v63, 1.0
	v_fma_f32 v71, -v50, v64, 1.0
	v_fma_f32 v73, -v54, v66, 1.0
	v_div_scale_f32 v47, s[16:17], v14, v30, v14
	v_div_scale_f32 v49, s[14:15], v15, v31, v15
	v_div_scale_f32 v51, s[12:13], v36, v32, v36
	v_div_scale_f32 v55, s[8:9], v41, v34, v41
	v_fmac_f32_e32 v62, v45, v62
	v_fmac_f32_e32 v63, v70, v63
	v_fmac_f32_e32 v64, v71, v64
	v_fmac_f32_e32 v66, v73, v66
	v_mul_f32_e32 v45, v47, v62
	v_mul_f32_e32 v70, v49, v63
	v_mul_f32_e32 v71, v51, v64
	v_mul_f32_e32 v73, v55, v66
	v_fma_f32 v78, -v46, v45, v47
	v_fma_f32 v79, -v48, v70, v49
	v_fma_f32 v80, -v50, v71, v51
	v_fma_f32 v82, -v54, v73, v55
	v_fmac_f32_e32 v45, v78, v62
	v_fmac_f32_e32 v70, v79, v63
	v_fmac_f32_e32 v71, v80, v64
	v_fmac_f32_e32 v73, v82, v66
	s_waitcnt lgkmcnt(0)
; __device__ __forceinline__ unsigned pk2(float lo, float hi) { unsigned r; asm("v_cvt_pk_bf16_f32 %0, %1, %2" : "=v"(r) : "v"(lo), "v"(hi)); return r; }
; __device__ __forceinline__ void gla_onorm_phase(const Ctx& c, int j) {
;     ...
;             const u32x4 a = *(const u32x4*)(P + (size_t)row * GLA_NP + col), bq = *(const u32x4*)(A + (size_t)row * DM + col), gq = *(const u32x4*)(P + (size_t)row * GLA_NP + 4096 + col);
;             const unsigned aw[4] = {a.x, a.y, a.z, a.w}, bw[4] = {bq.x, bq.y, bq.z, bq.w}, gw4[4] = {gq.x, gq.y, gq.z, gq.w};
;             float o[8], g[8]; float ss = 0.f;
; #pragma unroll
;             for (int e = 0; e < 4; ++e) {
;                 o[2 * e] = __uint_as_float(aw[e] << 16) + __uint_as_float(bw[e] << 16); o[2 * e + 1] = __uint_as_float(aw[e] & 0xffff0000u) + __uint_as_float(bw[e] & 0xffff0000u);
;                 g[2 * e] = __uint_as_float(gw4[e] << 16); g[2 * e + 1] = __uint_as_float(gw4[e] & 0xffff0000u);
;                 ss += o[2 * e] * o[2 * e] + o[2 * e + 1] * o[2 * e + 1]; }
;             const float rstd = 1.0f / sqrtf(wave_sum(ss) * (1.f / 512.f) + NORM_EPS);
;             float r[8];
; #pragma unroll
;             for (int e = 0; e < 8; ++e) r[e] = o[e] * rstd * w8[e] * (g[e] / (1.f + __expf(-g[e])));
;             u32x4 w; w.x = pk2(r[0], r[1]); w.y = pk2(r[2], r[3]); w.z = pk2(r[4], r[5]); w.w = pk2(r[6], r[7]);
;             *(u32x4*)(A + (size_t)row * DM + col) = w;
	v_add_f32_e32 v44, v44, v77
	v_fma_f32 v46, -v46, v45, v47
	v_fma_f32 v47, -v48, v70, v49
	v_fma_f32 v48, -v50, v71, v51
	v_fma_f32 v50, -v54, v73, v55
	ds_bpermute_b32 v54, v18, v44
	v_and_b32_e32 v38, 0xffff0000, v38
	v_and_b32_e32 v37, 0xffff0000, v37
	v_lshlrev_b32_e32 v43, 16, v39
	v_mul_f32_e32 v35, 0xbfb8aa3b, v38
	s_waitcnt lgkmcnt(0)
	v_add_f32_e32 v44, v44, v54
	ds_bpermute_b32 v54, v19, v44
	v_mul_f32_e32 v33, 0xbfb8aa3b, v37
	v_mul_f32_e32 v40, 0xbfb8aa3b, v43
	v_exp_f32_e32 v35, v35
	v_exp_f32_e32 v33, v33
	s_waitcnt lgkmcnt(0)
	v_add_f32_e32 v44, v44, v54
	ds_bpermute_b32 v54, v20, v44
	v_exp_f32_e32 v40, v40
	v_add_f32_e32 v35, 1.0, v35
	v_add_f32_e32 v33, 1.0, v33
	v_div_scale_f32 v56, s[2:3], v35, v35, v38
	s_waitcnt lgkmcnt(0)
	v_add_f32_e32 v44, v44, v54
	ds_bpermute_b32 v54, v21, v44
	v_add_f32_e32 v40, 1.0, v40
	v_div_scale_f32 v52, s[2:3], v33, v33, v37
	v_div_scale_f32 v58, s[2:3], v40, v40, v43
	v_rcp_f32_e32 v67, v56
	s_waitcnt lgkmcnt(0)
	v_add_f32_e32 v44, v44, v54
	v_rcp_f32_e32 v65, v52
	v_rcp_f32_e32 v68, v58
	v_fmamk_f32 v44, v44, 0x3b000000, v22
	v_mul_f32_e32 v54, 0x4f800000, v44
	v_cmp_gt_f32_e32 vcc, s21, v44
	v_fma_f32 v74, -v56, v67, 1.0
	v_div_scale_f32 v57, s[6:7], v38, v35, v38
	v_cndmask_b32_e32 v44, v44, v54, vcc
	v_sqrt_f32_e32 v54, v44
	v_fma_f32 v72, -v52, v65, 1.0
	v_fma_f32 v75, -v58, v68, 1.0
	v_fmac_f32_e32 v67, v74, v67
	v_div_scale_f32 v53, s[10:11], v37, v33, v37
	v_div_scale_f32 v59, s[4:5], v43, v40, v43
	v_fmac_f32_e32 v65, v72, v65
	v_fmac_f32_e32 v68, v75, v68
	v_mul_f32_e32 v74, v57, v67
	v_mul_f32_e32 v72, v53, v65
	v_mul_f32_e32 v75, v59, v68
	v_fma_f32 v83, -v56, v74, v57
	v_fma_f32 v81, -v52, v72, v53
	v_fma_f32 v84, -v58, v75, v59
	v_fmac_f32_e32 v74, v83, v67
	v_add_u32_e32 v55, -1, v54
	v_fmac_f32_e32 v72, v81, v65
	v_fmac_f32_e32 v75, v84, v68
	v_fma_f32 v51, -v56, v74, v57
	v_add_u32_e32 v56, 1, v54
	v_fma_f32 v57, -v55, v54, v44
	v_fma_f32 v49, -v52, v72, v53
	v_fma_f32 v52, -v58, v75, v59
	v_fma_f32 v58, -v56, v54, v44
	v_cmp_ge_f32_e64 s[18:19], 0, v57
	v_and_b32_e32 v39, 0xffff0000, v39
	v_mul_f32_e32 v42, 0xbfb8aa3b, v39
	v_cndmask_b32_e64 v54, v54, v55, s[18:19]
	v_cmp_lt_f32_e64 s[18:19], 0, v58
	v_exp_f32_e32 v42, v42
	s_nop 0
	v_cndmask_b32_e64 v54, v54, v56, s[18:19]
	v_mul_f32_e32 v55, 0x37800000, v54
	v_cndmask_b32_e32 v54, v54, v55, vcc
	v_cmp_class_f32_e32 vcc, v44, v23
	v_add_f32_e32 v42, 1.0, v42
	v_div_scale_f32 v60, s[2:3], v42, v42, v39
	v_cndmask_b32_e32 v44, v54, v44, vcc
	v_div_scale_f32 v54, s[18:19], v44, v44, 1.0
	v_rcp_f32_e32 v56, v54
	v_div_scale_f32 v55, vcc, 1.0, v44, 1.0
	v_rcp_f32_e32 v69, v60
	v_fma_f32 v57, -v54, v56, 1.0
	v_fmac_f32_e32 v56, v57, v56
	v_mul_f32_e32 v57, v55, v56
	v_fma_f32 v58, -v54, v57, v55
	v_fmac_f32_e32 v57, v58, v56
	v_fma_f32 v54, -v54, v57, v55
	v_div_fmas_f32 v54, v54, v56, v57
	s_mov_b64 vcc, s[16:17]
	v_div_fixup_f32 v44, v54, v44, 1.0
	v_div_fmas_f32 v45, v46, v62, v45
	s_mov_b64 vcc, s[14:15]
	v_fma_f32 v76, -v60, v69, 1.0
	v_div_fixup_f32 v14, v45, v30, v14
	v_mul_f32_e32 v11, v11, v44
	v_div_fmas_f32 v30, v47, v63, v70
	s_mov_b64 vcc, s[12:13]
	v_div_scale_f32 v61, s[2:3], v39, v42, v39
	v_fmac_f32_e32 v69, v76, v69
	v_mul_f32_e32 v10, v10, v44
	v_mul_f32_e32 v11, v1, v11
	v_div_fixup_f32 v15, v30, v31, v15
	v_div_fmas_f32 v30, v48, v64, v71
	s_mov_b64 vcc, s[10:11]
	v_mul_f32_e32 v76, v61, v69
	v_mul_f32_e32 v24, v24, v44
	v_mul_f32_e32 v25, v25, v44
	v_mul_f32_e32 v10, v0, v10
	v_mul_f32_e32 v11, v15, v11
	v_div_fmas_f32 v15, v49, v65, v72
	s_mov_b64 vcc, s[8:9]
	v_fma_f32 v85, -v60, v76, v61
	v_mul_f32_e32 v26, v26, v44
	v_mul_f32_e32 v24, v2, v24
	v_mul_f32_e32 v25, v3, v25
	v_mul_f32_e32 v10, v14, v10
	v_div_fixup_f32 v14, v30, v32, v36
	v_div_fixup_f32 v15, v15, v33, v37
	v_div_fmas_f32 v30, v50, v66, v73
	s_mov_b64 vcc, s[6:7]
	v_fmac_f32_e32 v76, v85, v69
	v_mul_f32_e32 v27, v27, v44
	v_mul_f32_e32 v26, v4, v26
	v_mul_f32_e32 v14, v14, v24
	v_cvt_pk_bf16_f32 v24, v10, v11
	v_mul_f32_e32 v10, v15, v25
	v_div_fixup_f32 v11, v30, v34, v41
	v_div_fmas_f32 v15, v51, v67, v74
	s_mov_b64 vcc, s[4:5]
	v_fma_f32 v53, -v60, v76, v61
	v_mul_f32_e32 v27, v5, v27
	v_mul_f32_e32 v11, v11, v26
	v_div_fixup_f32 v15, v15, v35, v38
	v_div_fmas_f32 v26, v52, v68, v75
	s_mov_b64 vcc, s[2:3]
	v_mul_f32_e32 v28, v28, v44
	v_mul_f32_e32 v29, v29, v44
	v_cvt_pk_bf16_f32 v25, v14, v10
	v_mul_f32_e32 v10, v15, v27
	v_div_fmas_f32 v15, v53, v69, v76
	v_mul_f32_e32 v28, v6, v28
	v_mul_f32_e32 v29, v7, v29
	v_div_fixup_f32 v14, v26, v40, v43
	v_div_fixup_f32 v15, v15, v42, v39
	v_mul_f32_e32 v14, v14, v28
	v_cvt_pk_bf16_f32 v26, v11, v10
	v_mul_f32_e32 v10, v15, v29
	v_cvt_pk_bf16_f32 v27, v14, v10
	global_store_dwordx4 v[12:13], v[24:27], off offset:3072
	s_cbranch_scc1 .LBB0_857

; #define LAS __attribute__((address_space(3)))
; template <int PH>
; __device__ __forceinline__ void run_phase(Ctx& c, LAS unsigned char* lds, char* lds_generic) {
;     ...
;         const bf16_t* Ap = (const bf16_t*)(c.ws + WS_A); const bf16_t* Bp = (const bf16_t*)(c.ws + (k == 1 ? WS_WIN : WS_WOUT)); bf16_t* Op = (bf16_t*)(c.ws + (k == 1 ? WS_P : WS_X));
;         {
;             constexpr int n_meta = 2 * (NFULL / 32), n_lr = (k == 1 && !attn) ? NREAL / 32 : 0;
;             const int r32 = c.lane & 31, hi = c.lane >> 5;
;             LAS float* RED = (LAS float*)lds;
;             for (int t = blockIdx.x; t < n_meta + n_lr; t += c.G) {
;                 const int row0 = t < n_meta ? NREAL + 32 * (t & 1) : 32 * (t - n_meta), col0 = t < n_meta ? 32 * (t >> 1) : ATT_N;
;                 const bf16_t* ap = Ap + (size_t)(row0 + r32) * DM + c.wave * 256 + hi * 64; const bf16_t* bp = Bp + (size_t)(col0 + r32) * DM + c.wave * 256 + hi * 64;
.LBB0_911:
	s_or_b64 exec, exec, s[2:3]
	s_waitcnt lgkmcnt(0)
	s_barrier
	s_nop 0
	s_nop 0
	s_nop 0
	s_nop 0
.LBB0_912:
	s_cmp_lt_i32 s74, 14
	s_cselect_b64 s[0:1], -1, 0
	s_cmp_gt_i32 s75, 13
	s_cselect_b64 s[2:3], -1, 0
	s_and_b64 s[0:1], s[0:1], s[2:3]
	s_andn2_b64 vcc, exec, s[0:1]
	s_cbranch_vccnz .LBB0_994
	s_add_u32 s38, s72, 0x2200000
	s_addc_u32 s39, s73, 0
	s_add_u32 s40, s72, 0x1a00000
	s_addc_u32 s41, s73, 0
	s_add_u32 s4, s72, 0x12500000
	v_mov_b32_e32 v0, v200
	s_addc_u32 s5, s73, 0
	s_cmpk_gt_i32 s76, 0x7f
	v_readfirstlane_b32 s0, v0
	s_cbranch_scc1 .LBB0_916
	s_ashr_i32 s6, s0, 6
	s_lshl_b32 s0, s6, 8
	s_ashr_i32 s1, s0, 31
	s_lshl_b64 s[0:1], s[0:1], 1
	s_add_u32 s2, s38, s0
	s_waitcnt vmcnt(0)
	v_and_b32_e32 v24, 31, v0
	v_bfe_u32 v1, v0, 5, 1
	s_addc_u32 s3, s39, s1
	v_lshlrev_b32_e32 v2, 9, v1
	v_lshlrev_b32_e32 v3, 2, v24
	v_lshlrev_b32_e32 v16, 7, v1
	v_mov_b32_e32 v17, 0
	s_add_u32 s0, s40, s0
	v_add3_u32 v2, 0, v2, v3
	v_lshl_add_u64 v[18:19], s[2:3], 0, v[16:17]
	s_addc_u32 s1, s41, s1
	s_lshl_b32 s2, s6, 12
	v_lshlrev_b32_e32 v1, 1, v0
	v_lshl_add_u32 v25, v0, 3, 0
	v_ashrrev_i32_e32 v26, 4, v0
	v_and_b32_e32 v0, 30, v1
	v_add_u32_e32 v27, s2, v2
	v_lshl_add_u64 v[20:21], s[0:1], 0, v[16:17]
	s_lshl_b32 s0, s76, 4
	s_lshl_b32 s1, s63, 4
	s_lshl_b32 s6, s76, 5
	s_lshl_b32 s7, s63, 5
	v_lshlrev_b32_e32 v22, 1, v0
	v_mov_b32_e32 v23, v17
	v_add_u32_e32 v28, 0x400, v27
	v_add_u32_e32 v29, 0x800, v27
	v_add_u32_e32 v30, 0xc00, v27
	s_mov_b32 s8, s76

; #define LAS __attribute__((address_space(3)))
; template <int PH>
; __device__ __forceinline__ void run_phase(Ctx& c, LAS unsigned char* lds, char* lds_generic) {
;     ...
;         const bf16_t* Ap = (const bf16_t*)(c.ws + WS_A); const bf16_t* Bp = (const bf16_t*)(c.ws + (k == 1 ? WS_WIN : WS_WOUT)); bf16_t* Op = (bf16_t*)(c.ws + (k == 1 ? WS_P : WS_X));
;         {
;             constexpr int n_meta = 2 * (NFULL / 32), n_lr = (k == 1 && !attn) ? NREAL / 32 : 0;
;             const int r32 = c.lane & 31, hi = c.lane >> 5;
;             LAS float* RED = (LAS float*)lds;
;             for (int t = blockIdx.x; t < n_meta + n_lr; t += c.G) {
;                 const int row0 = t < n_meta ? NREAL + 32 * (t & 1) : 32 * (t - n_meta), col0 = t < n_meta ? 32 * (t >> 1) : ATT_N;
;                 const bf16_t* ap = Ap + (size_t)(row0 + r32) * DM + c.wave * 256 + hi * 64; const bf16_t* bp = Bp + (size_t)(col0 + r32) * DM + c.wave * 256 + hi * 64;
.LBB0_1867:
	s_or_b64 exec, exec, s[2:3]
	s_waitcnt lgkmcnt(0)
	s_barrier
	s_nop 0
	s_nop 0
	s_nop 0
	s_nop 0
.LBB0_1868:
	s_cmp_lt_i32 s74, 30
	s_cselect_b64 s[0:1], -1, 0
	s_cmp_gt_i32 s75, 29
	s_cselect_b64 s[2:3], -1, 0
	s_and_b64 s[0:1], s[0:1], s[2:3]
	s_andn2_b64 vcc, exec, s[0:1]
	s_cbranch_vccnz .LBB0_1950
	s_add_u32 s38, s72, 0x2200000
	s_addc_u32 s39, s73, 0
	s_add_u32 s40, s72, 0x1a00000
	s_addc_u32 s41, s73, 0
	s_add_u32 s4, s72, 0x12500000
	v_mov_b32_e32 v0, v200
	s_addc_u32 s5, s73, 0
	s_cmpk_gt_i32 s76, 0x7f
	v_readfirstlane_b32 s0, v0
	s_cbranch_scc1 .LBB0_1872
	s_ashr_i32 s6, s0, 6
	s_lshl_b32 s0, s6, 8
	s_ashr_i32 s1, s0, 31
	s_lshl_b64 s[0:1], s[0:1], 1
	s_add_u32 s2, s38, s0
	s_waitcnt vmcnt(0)
	v_and_b32_e32 v24, 31, v0
	v_bfe_u32 v1, v0, 5, 1
	s_addc_u32 s3, s39, s1
	v_lshlrev_b32_e32 v2, 9, v1
	v_lshlrev_b32_e32 v3, 2, v24
	v_lshlrev_b32_e32 v16, 7, v1
	v_mov_b32_e32 v17, 0
	s_add_u32 s0, s40, s0
	v_add3_u32 v2, 0, v2, v3
	v_lshl_add_u64 v[18:19], s[2:3], 0, v[16:17]
	s_addc_u32 s1, s41, s1
	s_lshl_b32 s2, s6, 12
	v_lshlrev_b32_e32 v1, 1, v0
	v_lshl_add_u32 v25, v0, 3, 0
	v_ashrrev_i32_e32 v26, 4, v0
	v_and_b32_e32 v0, 30, v1
	v_add_u32_e32 v27, s2, v2
	v_lshl_add_u64 v[20:21], s[0:1], 0, v[16:17]
	s_lshl_b32 s0, s76, 4
	s_lshl_b32 s1, s63, 4
	s_lshl_b32 s6, s76, 5
	s_lshl_b32 s7, s63, 5
	v_lshlrev_b32_e32 v22, 1, v0
	v_mov_b32_e32 v23, v17
	v_add_u32_e32 v28, 0x400, v27
	v_add_u32_e32 v29, 0x800, v27
	v_add_u32_e32 v30, 0xc00, v27
	s_mov_b32 s8, s76
